# prep row loop: loop-invariant gamma and bias vectors loaded once before the loop (16 serialized load-wait round trips per iteration removed)
# speedup vs baseline: 1.0036x; 1.0010x over previous
; DEVQ unsigned pk2(float lo, float hi) { return f2bf(lo) | (f2bf(hi) << 16); }
; DEVQ void row_finish(const RowV& r, const float* g, bf16* urow, float* hcopy, const float* hbias, int lane) {
;     const float rstd = 1.0f / sqrtf(wave_sum(r.ss) * (1.0f / D) + RMS_EPS);
; #pragma unroll
;     for (int j = 0; j < 4; ++j) { const f32x4 gv = ((const f32x4*)g)[lane + 64 * j];
;         if (hcopy) ((f32x4*)hcopy)[lane + 64 * j] = r.v[j] + ((const f32x4*)hbias)[lane + 64 * j];
;         ((unsigned long long*)urow)[lane + 64 * j] = (unsigned long long)pk2(r.v[j].x * rstd * gv.x, r.v[j].y * rstd * gv.y) | ((unsigned long long)pk2(r.v[j].z * rstd * gv.z, r.v[j].w * rstd * gv.w) << 32); }
; }
; DEVQ void prep_phase(const Params& P, LAS unsigned char* lds, int gw, int ngw, int wave, int lane) {
;     ...
;     for (int m = 2 * gw; m < TPAD; m += 2 * ngw) {
;         const RowV ra = row_load(h0_src(P, m), lane), rb = row_load(h0_src(P, m + 1), lane);
;         row_finish(ra, P.in[3], U + (size_t)m * D, H + (size_t)m * D, P.in[19], lane);
;         row_finish(rb, P.in[3], U + (size_t)(m + 1) * D, H + (size_t)(m + 1) * D, P.in[19], lane);
;     }
.LBB0_803:
	s_cmp_gt_i32 s59, 0xa0ff
	s_cbranch_scc1 .LBB0_844
	s_waitcnt vmcnt(0)
	v_and_b32_e32 v0, 64, v185
	v_add_u32_e32 v0, 64, v0
	v_xor_b32_e32 v1, 1, v185
	v_cmp_lt_i32_e32 vcc, v1, v0
	v_readlane_b32 s4, v255, 35
	v_lshlrev_b32_e32 v128, 4, v136
	v_cndmask_b32_e32 v1, v185, v1, vcc
	v_lshlrev_b32_e32 v42, 2, v1
	v_xor_b32_e32 v1, 2, v185
	v_cmp_lt_i32_e32 vcc, v1, v0
	v_readlane_b32 s5, v255, 36
	s_lshl_b32 s0, s59, 1
	v_cndmask_b32_e32 v1, v185, v1, vcc
	v_lshlrev_b32_e32 v43, 2, v1
	v_xor_b32_e32 v1, 4, v185
	v_cmp_lt_i32_e32 vcc, v1, v0
	v_lshl_add_u64 v[32:33], s[4:5], 0, v[128:129]
	v_readlane_b32 s4, v255, 4
	v_cndmask_b32_e32 v1, v185, v1, vcc
	v_lshlrev_b32_e32 v44, 2, v1
	v_xor_b32_e32 v1, 8, v185
	v_readlane_b32 s5, v255, 5
	v_cmp_lt_i32_e32 vcc, v1, v0
	s_lshl_b32 s2, s24, 4
	v_lshl_add_u64 v[34:35], s[4:5], 0, v[128:129]
	v_readlane_b32 s4, v255, 37
	v_cndmask_b32_e32 v1, v185, v1, vcc
	v_readlane_b32 s5, v255, 38
	v_lshlrev_b32_e32 v45, 2, v1
	v_xor_b32_e32 v1, 16, v185
	v_readlane_b32 s5, v255, 17
	v_cmp_lt_i32_e32 vcc, v1, v0
	s_lshl_b32 s1, s4, 4
	s_lshl_b32 s3, s5, 1
	v_cndmask_b32_e32 v1, v185, v1, vcc
	s_add_i32 s1, s1, s3
	v_lshlrev_b32_e32 v46, 2, v1
	v_xor_b32_e32 v1, 32, v185
	s_add_i32 s14, s1, 0xfffefef0
	s_lshl_b32 s1, s4, 14
	s_lshl_b32 s3, s5, 11
	v_cmp_lt_i32_e32 vcc, v1, v0
	s_add_i32 s15, s1, s3
	s_ashr_i32 s1, s0, 31
	v_cndmask_b32_e32 v0, v185, v1, vcc
	s_lshl_b64 s[4:5], s[0:1], 11
	s_ashr_i32 s3, s2, 31
	s_lshl_b64 s[0:1], s[0:1], 12
	v_lshlrev_b32_e32 v47, 2, v0
	s_lshl_b32 s16, s24, 14
	v_lshl_or_b32 v36, v136, 3, s4
	v_mov_b32_e32 v37, s5
	s_lshl_b64 s[4:5], s[2:3], 11
	v_or_b32_e32 v38, s0, v128
	v_mov_b32_e32 v39, s1
	s_lshl_b64 s[6:7], s[2:3], 12
	v_readlane_b32 s19, v254, 42
	v_readlane_b32 s20, v254, 43
	v_readlane_b32 s21, v254, 44
	v_readlane_b32 s22, v254, 45
	v_readlane_b32 s23, v254, 46
	v_readlane_b32 s24, v254, 47
	flat_load_dwordx4 v[64:67], v[34:35]
	flat_load_dwordx4 v[68:71], v[32:33]
	flat_load_dwordx4 v[72:75], v[34:35] offset:1024
	flat_load_dwordx4 v[76:79], v[32:33] offset:1024
	flat_load_dwordx4 v[80:83], v[34:35] offset:2048
	flat_load_dwordx4 v[84:87], v[32:33] offset:2048
	flat_load_dwordx4 v[88:91], v[34:35] offset:3072
	flat_load_dwordx4 v[92:95], v[32:33] offset:3072
	s_branch .LBB0_806
.LBB0_805:
	s_waitcnt vmcnt(0) lgkmcnt(0)
	v_mul_f32_e32 v40, v29, v29
	v_mul_f32_e32 v41, v31, v31
	v_fmac_f32_e32 v40, v28, v28
	v_fmac_f32_e32 v41, v30, v30
	v_add_f32_e32 v40, v40, v41
	v_mul_f32_e32 v41, v21, v21
	v_mul_f32_e32 v48, v23, v23
	v_fmac_f32_e32 v41, v20, v20
	v_fmac_f32_e32 v48, v22, v22
	v_add_f32_e32 v41, v41, v48
	v_add_f32_e32 v40, v40, v41
	v_mul_f32_e32 v41, v25, v25
	v_mul_f32_e32 v48, v27, v27
	v_fmac_f32_e32 v41, v24, v24
	v_fmac_f32_e32 v48, v26, v26
	v_add_f32_e32 v41, v41, v48
	v_add_f32_e32 v40, v40, v41
	v_mul_f32_e32 v41, v13, v13
	v_mul_f32_e32 v52, v15, v15
	v_fmac_f32_e32 v41, v12, v12
	v_fmac_f32_e32 v52, v14, v14
	v_add_f32_e32 v41, v41, v52
	v_add_f32_e32 v40, v40, v41
	ds_bpermute_b32 v41, v42, v40
	s_mov_b32 s3, 0x3200000
	s_add_i32 s14, s14, s2
	s_add_i32 s15, s15, s16
	s_waitcnt lgkmcnt(0)
	v_add_f32_e32 v40, v40, v41
	ds_bpermute_b32 v41, v43, v40
	s_waitcnt lgkmcnt(0)
	v_add_f32_e32 v40, v40, v41
	ds_bpermute_b32 v41, v44, v40
	s_waitcnt lgkmcnt(0)
	v_add_f32_e32 v40, v40, v41
	ds_bpermute_b32 v41, v45, v40
	s_waitcnt lgkmcnt(0)
	v_add_f32_e32 v40, v40, v41
	ds_bpermute_b32 v41, v46, v40
	s_waitcnt lgkmcnt(0)
	v_add_f32_e32 v40, v40, v41
	ds_bpermute_b32 v41, v47, v40
	s_waitcnt lgkmcnt(0)
	v_add_f32_e32 v40, v40, v41
	v_fmamk_f32 v40, v40, 0x3a800000, v178
	v_mul_f32_e32 v41, 0x4f800000, v40
	v_cmp_gt_f32_e32 vcc, s28, v40
	v_pk_add_f32 v[50:51], v[30:31], v[66:67]
	v_cndmask_b32_e32 v56, v40, v41, vcc
	v_sqrt_f32_e32 v57, v56
	v_lshl_add_u64 v[40:41], s[66:67], 0, v[38:39]
	v_pk_add_f32 v[48:49], v[28:29], v[64:65]
	v_lshl_add_u64 v[38:39], v[38:39], 0, s[6:7]
	v_add_u32_e32 v58, -1, v57
	v_add_u32_e32 v59, 1, v57
	v_fma_f32 v60, -v58, v57, v56
	v_fma_f32 v61, -v59, v57, v56
	v_cmp_ge_f32_e64 s[0:1], 0, v60
	s_nop 1
	v_cndmask_b32_e64 v57, v57, v58, s[0:1]
	v_cmp_lt_f32_e64 s[0:1], 0, v61
	s_nop 1
	v_cndmask_b32_e64 v57, v57, v59, s[0:1]
	v_mul_f32_e32 v58, 0x37800000, v57
	v_cndmask_b32_e32 v57, v57, v58, vcc
	v_cmp_class_f32_e32 vcc, v56, v179
	s_nop 1
	v_cndmask_b32_e32 v58, v57, v56, vcc
	v_div_scale_f32 v59, s[0:1], v58, v58, 1.0
	v_rcp_f32_e32 v60, v59
	v_add_co_u32_e32 v56, vcc, s3, v40
	v_fma_f32 v62, -v59, v60, 1.0
	s_nop 0
	v_addc_co_u32_e32 v57, vcc, 0, v41, vcc
	v_div_scale_f32 v61, vcc, 1.0, v58, 1.0
	v_fmac_f32_e32 v60, v62, v60
	v_mul_f32_e32 v62, v61, v60
	v_fma_f32 v63, -v59, v62, v61
	v_fmac_f32_e32 v62, v63, v60
	v_fma_f32 v59, -v59, v62, v61
	v_div_fmas_f32 v59, v59, v60, v62
	v_div_fixup_f32 v58, v59, v58, 1.0
	v_mul_f32_e32 v59, v28, v58
	v_mul_f32_e32 v60, v29, v58
	v_mul_f32_e32 v28, v68, v59
	v_mul_f32_e32 v29, v69, v60
	flat_store_dwordx4 v[56:57], v[48:51]
	s_nop 1
	v_mul_f32_e32 v59, v22, v58
	v_mul_f32_e32 v60, v23, v58
	v_bfe_u32 v48, v28, 16, 1
	v_bfe_u32 v49, v29, 16, 1
	v_add3_u32 v28, v28, v48, s60
	v_lshrrev_b32_e32 v28, 16, v28
	v_add3_u32 v29, v29, v49, s60
	v_and_or_b32 v48, v29, s61, v28
	v_mul_f32_e32 v28, v30, v58
	v_mul_f32_e32 v28, v70, v28
	v_mul_f32_e32 v29, v31, v58
	v_mul_f32_e32 v29, v71, v29
	v_bfe_u32 v30, v28, 16, 1
	v_add3_u32 v28, v28, v30, s60
	v_bfe_u32 v30, v29, 16, 1
	v_lshrrev_b32_e32 v28, 16, v28
	v_add3_u32 v29, v29, v30, s60
	v_and_or_b32 v49, v29, s61, v28
	v_lshl_add_u64 v[28:29], s[66:67], 0, v[36:37]
	v_add_co_u32_e32 v28, vcc, s31, v28
	v_mul_f32_e32 v30, v20, v58
; DEVQ unsigned pk2(float lo, float hi) { return f2bf(lo) | (f2bf(hi) << 16); }
; DEVQ void row_finish(const RowV& r, const float* g, bf16* urow, float* hcopy, const float* hbias, int lane) {
;     const float rstd = 1.0f / sqrtf(wave_sum(r.ss) * (1.0f / D) + RMS_EPS);
; #pragma unroll
;     for (int j = 0; j < 4; ++j) { const f32x4 gv = ((const f32x4*)g)[lane + 64 * j];
;         if (hcopy) ((f32x4*)hcopy)[lane + 64 * j] = r.v[j] + ((const f32x4*)hbias)[lane + 64 * j];
;         ((unsigned long long*)urow)[lane + 64 * j] = (unsigned long long)pk2(r.v[j].x * rstd * gv.x, r.v[j].y * rstd * gv.y) | ((unsigned long long)pk2(r.v[j].z * rstd * gv.z, r.v[j].w * rstd * gv.w) << 32); }
; }
	s_nop 0
	v_addc_co_u32_e32 v29, vcc, 0, v29, vcc
	flat_store_dwordx2 v[28:29], v[48:49]
	s_nop 0
	v_mul_f32_e32 v31, v21, v58
	v_lshl_add_u64 v[36:37], v[36:37], 0, s[4:5]
	v_pk_add_f32 v[22:23], v[22:23], v[74:75]
	v_pk_add_f32 v[20:21], v[20:21], v[72:73]
	v_mul_f32_e32 v30, v76, v30
	v_mul_f32_e32 v48, v78, v59
	v_mul_f32_e32 v31, v77, v31
	v_mul_f32_e32 v49, v79, v60
	flat_store_dwordx4 v[56:57], v[20:23] offset:1024
	s_nop 1
	v_mul_f32_e32 v52, v26, v58
	v_mul_f32_e32 v53, v27, v58
	v_bfe_u32 v20, v30, 16, 1
	v_bfe_u32 v22, v48, 16, 1
	v_bfe_u32 v21, v31, 16, 1
	v_bfe_u32 v23, v49, 16, 1
	v_add3_u32 v20, v30, v20, s60
	v_add3_u32 v22, v48, v22, s60
	v_add3_u32 v21, v31, v21, s60
	v_add3_u32 v23, v49, v23, s60
	v_lshrrev_b32_e32 v20, 16, v20
	v_lshrrev_b32_e32 v22, 16, v22
	v_and_or_b32 v20, v21, s61, v20
	v_and_or_b32 v21, v23, s61, v22
	flat_store_dwordx2 v[28:29], v[20:21] offset:512
	s_nop 0
	v_mul_f32_e32 v30, v24, v58
	v_mul_f32_e32 v31, v25, v58
	v_pk_add_f32 v[22:23], v[26:27], v[82:83]
	v_pk_add_f32 v[20:21], v[24:25], v[80:81]
	v_mul_f32_e32 v24, v30, v84
	v_mul_f32_e32 v26, v52, v86
	v_mul_f32_e32 v25, v31, v85
	v_mul_f32_e32 v27, v53, v87
	flat_store_dwordx4 v[56:57], v[20:23] offset:2048
	s_nop 1
	v_mul_f32_e32 v30, v17, v17
	v_mul_f32_e32 v31, v19, v19
	v_bfe_u32 v20, v24, 16, 1
	v_bfe_u32 v22, v26, 16, 1
	v_bfe_u32 v21, v25, 16, 1
	v_bfe_u32 v23, v27, 16, 1
	v_add3_u32 v20, v24, v20, s60
	v_add3_u32 v22, v26, v22, s60
	v_add3_u32 v21, v25, v21, s60
	v_add3_u32 v23, v27, v23, s60
	v_lshrrev_b32_e32 v20, 16, v20
	v_lshrrev_b32_e32 v22, 16, v22
	v_and_or_b32 v20, v21, s61, v20
	v_and_or_b32 v21, v23, s61, v22
	flat_store_dwordx2 v[28:29], v[20:21] offset:1024
	s_nop 0
	v_mul_f32_e32 v48, v5, v5
	v_mul_f32_e32 v49, v7, v7
	v_mul_f32_e32 v50, v9, v9
	v_mul_f32_e32 v51, v11, v11
	v_fmac_f32_e32 v30, v16, v16
	v_fmac_f32_e32 v31, v18, v18
	v_fmac_f32_e32 v48, v4, v4
	v_fmac_f32_e32 v49, v6, v6
	v_mul_f32_e32 v52, v1, v1
	v_mul_f32_e32 v53, v3, v3
	v_fmac_f32_e32 v50, v8, v8
	v_fmac_f32_e32 v51, v10, v10
	v_add_f32_e32 v30, v30, v31
	v_add_f32_e32 v31, v48, v49
	v_fmac_f32_e32 v52, v0, v0
	v_fmac_f32_e32 v53, v2, v2
	v_add_f32_e32 v48, v50, v51
	v_add_f32_e32 v30, v30, v31
	v_add_f32_e32 v49, v52, v53
	v_add_f32_e32 v30, v30, v48
	v_add_f32_e32 v30, v30, v49
	v_mul_f32_e32 v31, v12, v58
	v_mul_f32_e32 v49, v14, v58
	v_mul_f32_e32 v48, v13, v58
	v_mul_f32_e32 v50, v15, v58
	v_pk_add_f32 v[14:15], v[14:15], v[90:91]
	v_pk_add_f32 v[12:13], v[12:13], v[88:89]
	v_mul_f32_e32 v20, v31, v92
	v_mul_f32_e32 v22, v49, v94
	v_mul_f32_e32 v21, v48, v93
	v_mul_f32_e32 v23, v50, v95
	flat_store_dwordx4 v[56:57], v[12:15] offset:3072
	s_nop 1
	ds_bpermute_b32 v24, v42, v30
	s_waitcnt lgkmcnt(0)
	v_add_f32_e32 v24, v30, v24
	v_bfe_u32 v12, v20, 16, 1
	v_bfe_u32 v14, v22, 16, 1
	v_bfe_u32 v13, v21, 16, 1
	v_bfe_u32 v15, v23, 16, 1
	v_add3_u32 v12, v20, v12, s60
	v_add3_u32 v14, v22, v14, s60
	v_add3_u32 v13, v21, v13, s60
	v_add3_u32 v15, v23, v15, s60
	v_lshrrev_b32_e32 v12, 16, v12
	v_lshrrev_b32_e32 v14, 16, v14
	v_and_or_b32 v12, v13, s61, v12
	v_and_or_b32 v13, v15, s61, v14
	flat_store_dwordx2 v[28:29], v[12:13] offset:1536
	ds_bpermute_b32 v25, v43, v24
	s_waitcnt lgkmcnt(0)
	v_add_f32_e32 v24, v24, v25
	ds_bpermute_b32 v25, v44, v24
	s_waitcnt lgkmcnt(0)
	v_add_f32_e32 v24, v24, v25
	ds_bpermute_b32 v25, v45, v24
	s_waitcnt lgkmcnt(0)
	v_add_f32_e32 v24, v24, v25
	ds_bpermute_b32 v25, v46, v24
	s_waitcnt lgkmcnt(0)
	v_add_f32_e32 v24, v24, v25
	ds_bpermute_b32 v25, v47, v24
	s_waitcnt lgkmcnt(0)
; DEVQ unsigned pk2(float lo, float hi) { return f2bf(lo) | (f2bf(hi) << 16); }
; DEVQ void row_finish(const RowV& r, const float* g, bf16* urow, float* hcopy, const float* hbias, int lane) {
;     const float rstd = 1.0f / sqrtf(wave_sum(r.ss) * (1.0f / D) + RMS_EPS);
; #pragma unroll
;     for (int j = 0; j < 4; ++j) { const f32x4 gv = ((const f32x4*)g)[lane + 64 * j];
;         if (hcopy) ((f32x4*)hcopy)[lane + 64 * j] = r.v[j] + ((const f32x4*)hbias)[lane + 64 * j];
;         ((unsigned long long*)urow)[lane + 64 * j] = (unsigned long long)pk2(r.v[j].x * rstd * gv.x, r.v[j].y * rstd * gv.y) | ((unsigned long long)pk2(r.v[j].z * rstd * gv.z, r.v[j].w * rstd * gv.w) << 32); }
; }
; DEVQ void prep_phase(const Params& P, LAS unsigned char* lds, int gw, int ngw, int wave, int lane) {
;     ...
;     for (int m = 2 * gw; m < TPAD; m += 2 * ngw) {
;         const RowV ra = row_load(h0_src(P, m), lane), rb = row_load(h0_src(P, m + 1), lane);
;         row_finish(ra, P.in[3], U + (size_t)m * D, H + (size_t)m * D, P.in[19], lane);
;         row_finish(rb, P.in[3], U + (size_t)(m + 1) * D, H + (size_t)(m + 1) * D, P.in[19], lane);
;     }
	v_add_f32_e32 v24, v24, v25
	v_fmamk_f32 v24, v24, 0x3a800000, v178
	v_mul_f32_e32 v25, 0x4f800000, v24
	v_cmp_gt_f32_e32 vcc, s28, v24
	v_pk_add_f32 v[14:15], v[18:19], v[66:67]
	v_cndmask_b32_e32 v24, v24, v25, vcc
	v_sqrt_f32_e32 v25, v24
	v_pk_add_f32 v[12:13], v[16:17], v[64:65]
	v_add_u32_e32 v26, -1, v25
	v_add_u32_e32 v27, 1, v25
	v_fma_f32 v30, -v26, v25, v24
	v_fma_f32 v31, -v27, v25, v24
	v_cmp_ge_f32_e64 s[0:1], 0, v30
	s_nop 1
	v_cndmask_b32_e64 v25, v25, v26, s[0:1]
	v_cmp_lt_f32_e64 s[0:1], 0, v31
	s_nop 1
	v_cndmask_b32_e64 v25, v25, v27, s[0:1]
	v_mul_f32_e32 v26, 0x37800000, v25
	v_cndmask_b32_e32 v25, v25, v26, vcc
	v_cmp_class_f32_e32 vcc, v24, v179
	s_nop 1
	v_cndmask_b32_e32 v26, v25, v24, vcc
	v_div_scale_f32 v27, s[0:1], v26, v26, 1.0
	v_rcp_f32_e32 v30, v27
	v_add_co_u32_e32 v24, vcc, s30, v40
	s_add_i32 s0, s14, 0x10110
	s_nop 0
	v_addc_co_u32_e32 v25, vcc, 0, v41, vcc
	v_fma_f32 v40, -v27, v30, 1.0
	v_div_scale_f32 v31, vcc, 1.0, v26, 1.0
	v_fmac_f32_e32 v30, v40, v30
	v_mul_f32_e32 v40, v31, v30
	v_fma_f32 v41, -v27, v40, v31
	v_fmac_f32_e32 v40, v41, v30
	v_fma_f32 v27, -v27, v40, v31
	v_div_fmas_f32 v27, v27, v30, v40
	v_div_fixup_f32 v26, v27, v26, 1.0
	v_mul_f32_e32 v27, v16, v26
	v_mul_f32_e32 v31, v18, v26
	v_mul_f32_e32 v30, v17, v26
	v_mul_f32_e32 v40, v19, v26
	v_mul_f32_e32 v16, v68, v27
	v_mul_f32_e32 v18, v70, v31
	v_mul_f32_e32 v17, v69, v30
	v_mul_f32_e32 v19, v71, v40
	flat_store_dwordx4 v[24:25], v[12:15]
	s_nop 1
	v_mul_f32_e32 v20, v4, v26
	v_mul_f32_e32 v22, v6, v26
	v_bfe_u32 v12, v16, 16, 1
	v_bfe_u32 v14, v18, 16, 1
	v_bfe_u32 v13, v17, 16, 1
	v_bfe_u32 v15, v19, 16, 1
	v_add3_u32 v12, v16, v12, s60
	v_add3_u32 v14, v18, v14, s60
	v_add3_u32 v13, v17, v13, s60
	v_add3_u32 v15, v19, v15, s60
	v_lshrrev_b32_e32 v12, 16, v12
	v_lshrrev_b32_e32 v14, 16, v14
	v_and_or_b32 v12, v13, s61, v12
	v_and_or_b32 v13, v15, s61, v14
	flat_store_dwordx2 v[28:29], v[12:13] offset:2048
	s_nop 0
	v_mul_f32_e32 v21, v5, v26
	v_mul_f32_e32 v23, v7, v26
	s_cmp_gt_i32 s0, 0x141ff
	v_pk_add_f32 v[6:7], v[6:7], v[74:75]
	v_pk_add_f32 v[4:5], v[4:5], v[72:73]
	v_mul_f32_e32 v12, v76, v20
	v_mul_f32_e32 v14, v78, v22
	v_mul_f32_e32 v13, v77, v21
	v_mul_f32_e32 v15, v79, v23
	flat_store_dwordx4 v[24:25], v[4:7] offset:1024
	s_nop 1
	v_mul_f32_e32 v16, v8, v26
	v_mul_f32_e32 v18, v10, v26
	v_bfe_u32 v4, v12, 16, 1
	v_bfe_u32 v6, v14, 16, 1
	v_bfe_u32 v5, v13, 16, 1
	v_bfe_u32 v7, v15, 16, 1
	v_add3_u32 v4, v12, v4, s60
	v_add3_u32 v6, v14, v6, s60
	v_add3_u32 v5, v13, v5, s60
	v_add3_u32 v7, v15, v7, s60
	v_lshrrev_b32_e32 v4, 16, v4
	v_lshrrev_b32_e32 v6, 16, v6
	v_and_or_b32 v4, v5, s61, v4
	v_and_or_b32 v5, v7, s61, v6
	flat_store_dwordx2 v[28:29], v[4:5] offset:2560
	s_nop 0
	v_mul_f32_e32 v17, v9, v26
	v_mul_f32_e32 v19, v11, v26
	v_pk_add_f32 v[6:7], v[10:11], v[82:83]
	v_pk_add_f32 v[4:5], v[8:9], v[80:81]
	v_mul_f32_e32 v8, v16, v84
	v_mul_f32_e32 v10, v18, v86
	v_mul_f32_e32 v9, v17, v85
	v_mul_f32_e32 v11, v19, v87
	flat_store_dwordx4 v[24:25], v[4:7] offset:2048
	s_nop 1
	v_mul_f32_e32 v12, v0, v26
	v_mul_f32_e32 v14, v2, v26
	v_bfe_u32 v4, v8, 16, 1
	v_bfe_u32 v6, v10, 16, 1
	v_bfe_u32 v5, v9, 16, 1
	v_bfe_u32 v7, v11, 16, 1
	v_add3_u32 v4, v8, v4, s60
	v_add3_u32 v6, v10, v6, s60
	v_add3_u32 v5, v9, v5, s60
	v_add3_u32 v7, v11, v7, s60
	v_lshrrev_b32_e32 v4, 16, v4
	v_lshrrev_b32_e32 v6, 16, v6
	v_and_or_b32 v4, v5, s61, v4
	v_and_or_b32 v5, v7, s61, v6
	flat_store_dwordx2 v[28:29], v[4:5] offset:3072
	s_nop 0
	v_mul_f32_e32 v13, v1, v26
	v_mul_f32_e32 v15, v3, v26
	v_pk_add_f32 v[2:3], v[2:3], v[90:91]
	v_pk_add_f32 v[0:1], v[0:1], v[88:89]
	v_mul_f32_e32 v4, v12, v92
	v_mul_f32_e32 v6, v14, v94
	v_mul_f32_e32 v5, v13, v93
	v_mul_f32_e32 v7, v15, v95
	flat_store_dwordx4 v[24:25], v[0:3] offset:3072
	s_nop 1
	s_nop 1
	v_bfe_u32 v0, v4, 16, 1
	v_bfe_u32 v2, v6, 16, 1
	v_bfe_u32 v1, v5, 16, 1
	v_bfe_u32 v3, v7, 16, 1
	v_add3_u32 v0, v4, v0, s60
	v_add3_u32 v2, v6, v2, s60
	v_add3_u32 v1, v5, v1, s60
	v_add3_u32 v3, v7, v3, s60
	v_lshrrev_b32_e32 v0, 16, v0
	v_lshrrev_b32_e32 v2, 16, v2
	v_and_or_b32 v0, v1, s61, v0
	v_and_or_b32 v1, v3, s61, v2
	flat_store_dwordx2 v[28:29], v[0:1] offset:3584
	s_cbranch_scc1 .LBB0_844
